# HGRN scan: helper waves also stage token-transposed Kt/V; compute waves fetch MFMA operands with ds_read_b64 instead of u16 gathers
# speedup vs baseline: 1.0202x; 1.0039x over previous
; DI void hgrn_scan_mfma(const Params& p, char* shm) {
;     ...
;         for (int kt = 0; kt < 8; ++kt) S[kt] = (f32x4){0.f, 0.f, 0.f, 0.f};
;         const int lt = tid >> 4, lp = tid & 15;
;         u32x4 ra0, ra1, ra2, ra3, ra4, rb0, rb1, rb2, rb3, rb4;
;     ...
;         HG_LOAD(0, ra0, ra1, ra2, ra3, ra4); HG_LOAD(1, rb0, rb1, rb2, rb3, rb4);
;         for (int ch2 = 0; ch2 < LT / C; ch2 += 2) {
; #pragma unroll
;           for (int hh = 0; hh < 2; ++hh) {
;             const int ch = ch2 + hh;
;             if (hh == 0) HG_STAGE(ch, ra0, ra1, ra2, ra3, ra4); else HG_STAGE(ch, rb0, rb1, rb2, rb3, rb4);
;             { const bf16_t* kt16 = (const bf16_t*)KtL; const bf16_t* v16 = (const bf16_t*)VL; const int vcol = w * 16 + l15;
;     ...
;               const bf16x8 vf = __builtin_bit_cast(bf16x8, (u32x4){HG_U2(v16, g * 4 + 0, g * 4 + 1, vcol), HG_U2(v16, g * 4 + 2, g * 4 + 3, vcol), HG_U2(v16, 16 + g * 4 + 0, 16 + g * 4 + 1, vcol), HG_U2(v16, 16 + g * 4 + 2, 16 + g * 4 + 3, vcol)});
;               f32x4 sc00 = (f32x4){0.f, 0.f, 0.f, 0.f}, sc01 = sc00, sc11 = sc00, o0 = sc00, o1 = sc00;
; #pragma unroll
;               for (int kc = 0; kc < 4; ++kc) {
;                   const bf16x8 aK0 = *(const bf16x8*)(KtL + l15 * QS + kc * 64 + g * 16), aK1 = *(const bf16x8*)(KtL + (16 + l15) * QS + kc * 64 + g * 16);
;                   const bf16x8 bQ0 = *(const bf16x8*)(QtL + l15 * QS + kc * 64 + g * 16), bQ1 = *(const bf16x8*)(QtL + (16 + l15) * QS + kc * 64 + g * 16);
;                   sc00 = __builtin_amdgcn_mfma_f32_16x16x32_bf16(aK0, bQ0, sc00, 0, 0, 0);
;                   sc01 = __builtin_amdgcn_mfma_f32_16x16x32_bf16(aK0, bQ1, sc01, 0, 0, 0);
;                   sc11 = __builtin_amdgcn_mfma_f32_16x16x32_bf16(aK1, bQ1, sc11, 0, 0, 0);
;                   const int kp = kc;
;                   const u32x2 qa0 = *(const u32x2*)(QtL + l15 * QS + ((2 * kp) * 16 + g * 4) * 2), qb0 = *(const u32x2*)(QtL + l15 * QS + ((2 * kp + 1) * 16 + g * 4) * 2);
;                   const u32x2 qa1 = *(const u32x2*)(QtL + (16 + l15) * QS + ((2 * kp) * 16 + g * 4) * 2), qb1 = *(const u32x2*)(QtL + (16 + l15) * QS + ((2 * kp + 1) * 16 + g * 4) * 2);
;                   const bf16x8 sw = __builtin_bit_cast(bf16x8, (u32x4){pack2(S[2 * kp][0], S[2 * kp][1]), pack2(S[2 * kp][2], S[2 * kp][3]), pack2(S[2 * kp + 1][0], S[2 * kp + 1][1]), pack2(S[2 * kp + 1][2], S[2 * kp + 1][3])});
.LBB0_2416:
	s_or_b64 exec, exec, s[14:15]
	v_cndmask_b32_e64 v3, 0, 1, s[40:41]
	v_lshl_add_u64 v[142:143], s[0:1], 0, v[0:1]
	v_readfirstlane_b32 s14, v3
	s_lshl_b32 s55, s14, 3
	s_lshl_b32 s14, s31, 2
	s_and_b32 s56, s14, 0xe00
	s_and_b64 s[14:15], s[12:13], exec
	s_cselect_b32 s14, s72, 0x146da000
	s_add_u32 s14, s68, s14
	s_addc_u32 s15, s69, 0
	s_add_u32 s14, s14, s38
	s_addc_u32 s15, s15, 0
	v_lshl_add_u64 v[132:133], v[120:121], 1, s[14:15]
	s_and_b64 s[14:15], s[12:13], exec
	s_cselect_b32 s15, 0, -1
	s_cselect_b32 s14, s73, 0xfffffc00
	s_add_i32 s0, s54, s55
	s_mul_hi_i32 s1, s0, 0x48000
	s_mul_i32 s0, s0, 0x48000
	s_or_b32 s0, s0, s56
	v_mov_b32_e32 v44, 0
	s_mov_b32 s74, 0
	v_lshl_add_u64 v[128:129], v[116:117], 0, s[38:39]
	v_lshl_add_u64 v[130:131], v[118:119], 0, s[38:39]
	v_mul_hi_i32_i24_e32 v135, s14, v147
	v_mul_i32_i24_e32 v134, s14, v147
	s_lshl_b64 s[52:53], s[14:15], 5
	v_mul_hi_i32_i24_e32 v137, s14, v152
	v_mul_i32_i24_e32 v136, s14, v152
	v_mul_hi_i32_i24_e32 v139, s14, v153
	v_mul_i32_i24_e32 v138, s14, v153
	v_mul_hi_i32_i24_e32 v141, s14, v154
	v_mul_i32_i24_e32 v140, s14, v154
	v_lshl_add_u64 v[144:145], v[122:123], 0, s[0:1]
	s_movk_i32 s38, 0xffe0
	s_mov_b32 s76, 0
	v_mov_b32_e32 v45, v44
	v_mov_b32_e32 v46, v44
	v_mov_b32_e32 v47, v44
	v_mov_b32_e32 v48, v44
	v_mov_b32_e32 v49, v44
	v_mov_b32_e32 v50, v44
	v_mov_b32_e32 v51, v44
	v_mov_b32_e32 v52, v44
	v_mov_b32_e32 v53, v44
	v_mov_b32_e32 v54, v44
	v_mov_b32_e32 v55, v44
	v_mov_b32_e32 v56, v44
	v_mov_b32_e32 v57, v44
	v_mov_b32_e32 v58, v44
	v_mov_b32_e32 v59, v44
	v_mov_b32_e32 v60, v44
	v_mov_b32_e32 v61, v44
	v_mov_b32_e32 v62, v44
	v_mov_b32_e32 v63, v44
	v_mov_b32_e32 v64, v44
	v_mov_b32_e32 v65, v44
	v_mov_b32_e32 v66, v44
	v_mov_b32_e32 v67, v44
	v_mov_b32_e32 v72, v44
	v_mov_b32_e32 v73, v44
	v_mov_b32_e32 v74, v44
	v_mov_b32_e32 v75, v44
	v_mov_b32_e32 v68, v44
	v_mov_b32_e32 v69, v44
	v_mov_b32_e32 v70, v44
	v_mov_b32_e32 v71, v44
	s_cmp_lg_u32 s100, 0
	s_cbranch_scc1 .Lscanh_pro
	v_add_u32_e32 v195, 0x8000, v161
	v_add_u32_e32 v197, 0x9000, v161
	v_and_b32_e32 v200, 15, v252
	v_bfe_u32 v201, v252, 4, 2
	v_lshlrev_b32_e32 v201, 3, v201
	v_lshrrev_b32_e32 v202, 3, v200
	v_mul_u32_u24_e32 v199, 0x50, v200
	v_lshl_add_u32 v199, v202, 3, v199
	v_add_u32_e32 v199, v199, v201
	v_add_u32_e32 v199, 0x10000, v199
	v_lshrrev_b32_e32 v202, 3, v120
	v_mul_u32_u24_e32 v198, 0x50, v120
	v_lshl_add_u32 v198, v202, 3, v198
	v_add_u32_e32 v198, v198, v201
	v_add_u32_e32 v198, 0x10000, v198
.LBB0_2417:
	s_nop 0
	s_barrier
	s_and_saveexec_b64 s[0:1], s[2:3]
	s_or_b64 exec, exec, s[0:1]
	s_add_i32 s75, s76, 2
	s_cmpk_lt_u32 s76, 0x46
	s_cselect_b64 s[56:57], -1, 0
	s_cmpk_gt_u32 s76, 0x45
	s_cselect_b64 s[54:55], -1, 0
	s_and_b64 vcc, exec, s[54:55]
	s_branch .LBB0_2429
.LBB0_2429:
	ds_read_b128 v[80:83], v160 offset:17408
	ds_read_b128 v[76:79], v160
	ds_read_b128 v[84:87], v160 offset:21760
	ds_read_b128 v[88:91], v160 offset:17472
	ds_read_b128 v[92:95], v160 offset:64
	ds_read_b128 v[96:99], v160 offset:4352
	ds_read_b128 v[100:103], v160 offset:21824
	ds_read_b128 v[104:107], v160 offset:4416
	s_waitcnt lgkmcnt(6)
	v_mfma_f32_16x16x32_bf16 v[76:79], v[80:83], v[76:79], 0
	v_cvt_pk_bf16_f32 v186, v52, v53
	v_cvt_pk_bf16_f32 v187, v54, v55
	v_cvt_pk_bf16_f32 v188, v56, v57
	s_waitcnt lgkmcnt(3)
	v_mfma_f32_16x16x32_bf16 v[76:79], v[88:91], v[92:95], v[76:79]
	ds_read_b128 v[92:95], v160 offset:17536
	ds_read_b128 v[108:111], v160 offset:128
	v_cvt_pk_bf16_f32 v189, v58, v59
	s_cmp_lt_u32 s76, 8
	s_waitcnt lgkmcnt(4)
	v_mfma_f32_16x16x32_bf16 v[84:87], v[84:87], v[96:99], 0
	s_cselect_b32 s77, 0xff, s58
	s_add_i32 s77, s77, s38
	s_add_i32 s78, s77, 32
	s_waitcnt lgkmcnt(2)
	v_mfma_f32_16x16x32_bf16 v[84:87], v[100:103], v[104:107], v[84:87]
	ds_read_b128 v[100:103], v160 offset:21888
	ds_read_b128 v[162:165], v160 offset:17600
	ds_read_b128 v[166:169], v160 offset:192
	ds_read_b128 v[170:173], v160 offset:4480
	ds_read_b128 v[174:177], v160 offset:21952
	ds_read_b128 v[178:181], v160 offset:4544
	s_and_b64 s[14:15], s[12:13], exec
	s_waitcnt lgkmcnt(6)
	v_mfma_f32_16x16x32_bf16 v[108:111], v[92:95], v[108:111], v[76:79]
	ds_read_b64 v[76:77], v198 offset:10368
	ds_read_b64 v[78:79], v198 offset:10400
	v_mov_b32_e32 v0, s39
	s_waitcnt lgkmcnt(4)
	v_mfma_f32_16x16x32_bf16 v[84:87], v[100:103], v[170:173], v[84:87]
	v_add_u32_e32 v125, 0x1000, v161
	v_mfma_f32_16x16x32_bf16 v[100:103], v[162:165], v[166:169], v[108:111]
	ds_read2_b64 v[166:169], v125 offset0:32 offset1:36
	s_cselect_b32 s14, s74, s78
	ds_read2_b64 v[108:111], v161 offset1:4
	v_mfma_f32_16x16x32_bf16 v[80:83], v[80:83], v[96:99], 0
	s_nop 2
	s_nop 0
	v_cndmask_b32_e64 v0, v100, v0, s[4:5]
	v_cndmask_b32_e64 v0, v0, v100, s[6:7]
	v_cndmask_b32_e64 v3, v102, 0, s[8:9]
	s_waitcnt lgkmcnt(4)
	v_mfma_f32_16x16x32_bf16 v[84:87], v[174:177], v[178:181], v[84:87]
	v_cvt_pk_bf16_f32 v174, v44, v45
	v_cvt_pk_bf16_f32 v175, v46, v47
	v_cvt_pk_bf16_f32 v176, v48, v49
	v_cvt_pk_bf16_f32 v177, v50, v51
	v_mfma_f32_16x16x32_bf16 v[80:83], v[88:91], v[104:107], v[80:83]
	s_add_u32 s14, s50, s14
	s_addc_u32 s15, s51, 0
	s_lshl_b64 s[14:15], s[14:15], 11
	s_waitcnt lgkmcnt(0)
	v_mfma_f32_16x16x32_bf16 v[96:99], v[108:111], v[174:177], 0
	ds_read2_b64 v[108:111], v161 offset0:8 offset1:12
	ds_read2_b64 v[182:185], v125 offset0:40 offset1:44
	ds_read2_b64 v[88:91], v161 offset0:16 offset1:20
	ds_read2_b64 v[104:107], v125 offset0:48 offset1:52
	v_mfma_f32_16x16x32_bf16 v[166:169], v[166:169], v[174:177], 0
	v_cvt_pk_bf16_f32 v174, v60, v61
	v_cvt_pk_bf16_f32 v175, v62, v63
	v_cvt_pk_bf16_f32 v176, v64, v65
	s_waitcnt lgkmcnt(3)
; DI void hgrn_scan_mfma(const Params& p, char* shm) {
;     ...
;                   const u32x2 qa0 = *(const u32x2*)(QtL + l15 * QS + ((2 * kp) * 16 + g * 4) * 2), qb0 = *(const u32x2*)(QtL + l15 * QS + ((2 * kp + 1) * 16 + g * 4) * 2);
;                   const u32x2 qa1 = *(const u32x2*)(QtL + (16 + l15) * QS + ((2 * kp) * 16 + g * 4) * 2), qb1 = *(const u32x2*)(QtL + (16 + l15) * QS + ((2 * kp + 1) * 16 + g * 4) * 2);
;                   const bf16x8 sw = __builtin_bit_cast(bf16x8, (u32x4){pack2(S[2 * kp][0], S[2 * kp][1]), pack2(S[2 * kp][2], S[2 * kp][3]), pack2(S[2 * kp + 1][0], S[2 * kp + 1][1]), pack2(S[2 * kp + 1][2], S[2 * kp + 1][3])});
;                   o0 = __builtin_amdgcn_mfma_f32_16x16x32_bf16(__builtin_bit_cast(bf16x8, (u32x4){qa0.x, qa0.y, qb0.x, qb0.y}), sw, o0, 0, 0, 0);
;                   o1 = __builtin_amdgcn_mfma_f32_16x16x32_bf16(__builtin_bit_cast(bf16x8, (u32x4){qa1.x, qa1.y, qb1.x, qb1.y}), sw, o1, 0, 0, 0); }
; #pragma unroll
;               for (int r = 0; r < 4; ++r) if (g * 4 + r > l15) { sc00[r] = 0.f; sc11[r] = 0.f; }
;               o0 = __builtin_amdgcn_mfma_f32_16x16x32_bf16(__builtin_bit_cast(bf16x8, (u32x4){pack2(sc00[0], sc00[1]), pack2(sc00[2], sc00[3]), 0u, 0u}), vf, o0, 0, 0, 0);
;               o1 = __builtin_amdgcn_mfma_f32_16x16x32_bf16(__builtin_bit_cast(bf16x8, (u32x4){pack2(sc01[0], sc01[1]), pack2(sc01[2], sc01[3]), pack2(sc11[0], sc11[1]), pack2(sc11[2], sc11[3])}), vf, o1, 0, 0, 0);
; #pragma unroll
;               for (int r = 0; r < 4; ++r) {
;                   const long rb_ = (long)HG_ROW(b, dir, ch * C), st_ = dir ? -(long)D : (long)D; bf16_t* op_ = Oo + rb_ * D + head * 128 + vcol + (long)(g * 4 + r) * st_;
;                   op_[0] = (bf16_t)(pack2(o0[r], 0.f) & 0xffffu); op_[16 * st_] = (bf16_t)(pack2(o1[r], 0.f) & 0xffffu); }
; #pragma unroll
;               for (int kt = 0; kt < 8; ++kt) { const f32x4 dcy = *(const f32x4*)(eBL + kt * 16 + g * 4); const int kcol = kt * 16 + l15;
;                   const bf16x8 kl = __builtin_bit_cast(bf16x8, (u32x4){HG_U2(kt16, g * 4 + 0, g * 4 + 1, kcol), HG_U2(kt16, g * 4 + 2, g * 4 + 3, kcol), HG_U2(kt16, 16 + g * 4 + 0, 16 + g * 4 + 1, kcol), HG_U2(kt16, 16 + g * 4 + 2, 16 + g * 4 + 3, kcol)});
;                   S[kt] = __builtin_amdgcn_mfma_f32_16x16x32_bf16(kl, vf, S[kt], 0, 0, 0) * dcy; }
	v_mfma_f32_16x16x32_bf16 v[96:99], v[108:111], v[186:189], v[96:99]
	v_cvt_pk_bf16_f32 v177, v66, v67
	v_mfma_f32_16x16x32_bf16 v[80:83], v[92:95], v[170:173], v[80:83]
	v_mov_b32_e32 v92, s39
	v_cndmask_b32_e64 v1, v84, v92, s[4:5]
	s_waitcnt lgkmcnt(2)
	v_mfma_f32_16x16x32_bf16 v[108:111], v[182:185], v[186:189], v[166:169]
	s_nop 2
	ds_read2_b64 v[166:169], v161 offset0:24 offset1:28
	ds_read2_b64 v[182:185], v125 offset0:56 offset1:60
	v_cvt_pk_bf16_f32 v186, v72, v73
	v_cvt_pk_bf16_f32 v187, v74, v75
	s_waitcnt lgkmcnt(3)
	v_mfma_f32_16x16x32_bf16 v[88:91], v[88:91], v[174:177], v[96:99]
	v_cvt_pk_bf16_f32 v188, v68, v69
	v_cvt_pk_bf16_f32 v189, v70, v71
	v_mfma_f32_16x16x32_bf16 v[80:83], v[162:165], v[178:181], v[80:83]
	v_cndmask_b32_e64 v96, v1, v84, s[6:7]
	v_cndmask_b32_e64 v1, 0, v101, s[6:7]
	v_cndmask_b32_e64 v84, v103, 0, s[10:11]
	s_waitcnt lgkmcnt(2)
	v_mfma_f32_16x16x32_bf16 v[92:95], v[104:107], v[174:177], v[108:111]
	v_cvt_pk_bf16_f32 v0, v0, v1
	v_cvt_pk_bf16_f32 v1, v3, v84
	v_mov_b32_e32 v3, v2
	v_cndmask_b32_e64 v97, 0, v85, s[6:7]
	v_cndmask_b32_e64 v98, v86, 0, s[8:9]
	v_cndmask_b32_e64 v99, v87, 0, s[10:11]
	s_waitcnt lgkmcnt(1)
	v_mfma_f32_16x16x32_bf16 v[88:91], v[166:169], v[186:189], v[88:91]
	v_cvt_pk_bf16_f32 v80, v80, v81
	v_cvt_pk_bf16_f32 v81, v82, v83
	v_cvt_pk_bf16_f32 v82, v96, v97
	v_cvt_pk_bf16_f32 v83, v98, v99
	s_waitcnt lgkmcnt(0)
	v_mfma_f32_16x16x32_bf16 v[92:95], v[182:185], v[186:189], v[92:95]
	v_mfma_f32_16x16x32_bf16 v[84:87], v[0:3], v[76:79], v[88:91]
	v_lshl_add_u64 v[0:1], v[132:133], 0, s[14:15]
	v_mfma_f32_16x16x32_bf16 v[80:83], v[80:83], v[76:79], v[92:95]
	s_nop 0
	v_lshl_add_u64 v[88:89], v[134:135], 1, v[0:1]
	s_nop 3
	v_cvt_pk_bf16_f32 v3, v84, s0
	global_store_short v[88:89], v3, off
	v_lshl_add_u64 v[88:89], v[88:89], 0, s[52:53]
	v_cvt_pk_bf16_f32 v3, v80, s0
	global_store_short v[88:89], v3, off
	v_lshl_add_u64 v[88:89], v[136:137], 1, v[0:1]
	v_cvt_pk_bf16_f32 v3, v85, s0
	global_store_short v[88:89], v3, off
	v_cvt_pk_bf16_f32 v3, v81, s0
	v_lshl_add_u64 v[80:81], v[88:89], 0, s[52:53]
	global_store_short v[80:81], v3, off
	v_lshl_add_u64 v[80:81], v[138:139], 1, v[0:1]
	v_cvt_pk_bf16_f32 v3, v86, s0
	global_store_short v[80:81], v3, off
	ds_read_b64 v[200:201], v199 offset:0
	ds_read_b64 v[202:203], v199 offset:32
	ds_read_b64 v[204:205], v199 offset:1296
	ds_read_b64 v[206:207], v199 offset:1328
	ds_read_b64 v[208:209], v199 offset:2592
	ds_read_b64 v[210:211], v199 offset:2624
	ds_read_b64 v[212:213], v199 offset:3888
	ds_read_b64 v[214:215], v199 offset:3920
	ds_read_b64 v[216:217], v199 offset:5184
	ds_read_b64 v[218:219], v199 offset:5216
	ds_read_b64 v[220:221], v199 offset:6480
	ds_read_b64 v[222:223], v199 offset:6512
	ds_read_b64 v[224:225], v199 offset:7776
	ds_read_b64 v[226:227], v199 offset:7808
	ds_read_b64 v[228:229], v199 offset:9072
	ds_read_b64 v[230:231], v199 offset:9104
	s_waitcnt lgkmcnt(14)
	v_mfma_f32_16x16x32_bf16 v[44:47], v[200:203], v[76:79], v[44:47]
	v_cvt_pk_bf16_f32 v3, v82, s0
	v_lshl_add_u64 v[80:81], v[80:81], 0, s[52:53]
	global_store_short v[80:81], v3, off
	v_lshl_add_u64 v[0:1], v[140:141], 1, v[0:1]
	v_cvt_pk_bf16_f32 v3, v87, s0
	s_waitcnt lgkmcnt(12)
	v_mfma_f32_16x16x32_bf16 v[48:51], v[204:207], v[76:79], v[48:51]
	s_waitcnt lgkmcnt(10)
	v_mfma_f32_16x16x32_bf16 v[52:55], v[208:211], v[76:79], v[52:55]
	global_store_short v[0:1], v3, off
	v_cvt_pk_bf16_f32 v3, v83, s0
	v_lshl_add_u64 v[0:1], v[0:1], 0, s[52:53]
	s_waitcnt lgkmcnt(8)
	v_mfma_f32_16x16x32_bf16 v[56:59], v[212:215], v[76:79], v[56:59]
	global_store_short v[0:1], v3, off
	s_waitcnt lgkmcnt(6)
	v_mfma_f32_16x16x32_bf16 v[60:63], v[216:219], v[76:79], v[60:63]
	ds_read_b128 v[108:111], v149 offset:26112
	ds_read_b128 v[104:107], v149 offset:26176
	ds_read_b128 v[100:103], v149 offset:26240
	ds_read_b128 v[96:99], v149 offset:26304
	s_waitcnt lgkmcnt(8)
	v_mfma_f32_16x16x32_bf16 v[64:67], v[220:223], v[76:79], v[64:67]
	s_waitcnt lgkmcnt(6)
	v_mfma_f32_16x16x32_bf16 v[80:83], v[224:227], v[76:79], v[72:75]
	ds_read_b128 v[92:95], v149 offset:26368
	ds_read_b128 v[88:91], v149 offset:26432
	ds_read_b128 v[84:87], v149 offset:26496
	ds_read_b128 v[72:75], v149 offset:26560
	s_waitcnt lgkmcnt(0)
	s_barrier
	v_mfma_f32_16x16x32_bf16 v[76:79], v[228:231], v[76:79], v[68:71]
	s_nop 0
	s_nop 0
	s_and_saveexec_b64 s[14:15], s[2:3]
	s_or_b64 exec, exec, s[14:15]
	s_andn2_b64 vcc, exec, s[56:57]
	s_branch .LBB0_2441
; DI unsigned pack2(float lo, float hi) { const f32x2 v = (f32x2){lo, hi}; return __builtin_bit_cast(unsigned, __builtin_convertvector(v, bf16x2_t)); }
; DI void hgrn_scan_mfma(const Params& p, char* shm) {
;     ...
;             { const bf16_t* kt16 = (const bf16_t*)KtL; const bf16_t* v16 = (const bf16_t*)VL; const int vcol = w * 16 + l15;
;     ...
;               const bf16x8 vf = __builtin_bit_cast(bf16x8, (u32x4){HG_U2(v16, g * 4 + 0, g * 4 + 1, vcol), HG_U2(v16, g * 4 + 2, g * 4 + 3, vcol), HG_U2(v16, 16 + g * 4 + 0, 16 + g * 4 + 1, vcol), HG_U2(v16, 16 + g * 4 + 2, 16 + g * 4 + 3, vcol)});
;               f32x4 sc00 = (f32x4){0.f, 0.f, 0.f, 0.f}, sc01 = sc00, sc11 = sc00, o0 = sc00, o1 = sc00;
; #pragma unroll
;               for (int kc = 0; kc < 4; ++kc) {
;                   const bf16x8 aK0 = *(const bf16x8*)(KtL + l15 * QS + kc * 64 + g * 16), aK1 = *(const bf16x8*)(KtL + (16 + l15) * QS + kc * 64 + g * 16);
;                   const bf16x8 bQ0 = *(const bf16x8*)(QtL + l15 * QS + kc * 64 + g * 16), bQ1 = *(const bf16x8*)(QtL + (16 + l15) * QS + kc * 64 + g * 16);
;                   sc00 = __builtin_amdgcn_mfma_f32_16x16x32_bf16(aK0, bQ0, sc00, 0, 0, 0);
;                   sc01 = __builtin_amdgcn_mfma_f32_16x16x32_bf16(aK0, bQ1, sc01, 0, 0, 0);
;                   sc11 = __builtin_amdgcn_mfma_f32_16x16x32_bf16(aK1, bQ1, sc11, 0, 0, 0);
;                   const int kp = kc;
;                   const u32x2 qa0 = *(const u32x2*)(QtL + l15 * QS + ((2 * kp) * 16 + g * 4) * 2), qb0 = *(const u32x2*)(QtL + l15 * QS + ((2 * kp + 1) * 16 + g * 4) * 2);
;                   const u32x2 qa1 = *(const u32x2*)(QtL + (16 + l15) * QS + ((2 * kp) * 16 + g * 4) * 2), qb1 = *(const u32x2*)(QtL + (16 + l15) * QS + ((2 * kp + 1) * 16 + g * 4) * 2);
;                   const bf16x8 sw = __builtin_bit_cast(bf16x8, (u32x4){pack2(S[2 * kp][0], S[2 * kp][1]), pack2(S[2 * kp][2], S[2 * kp][3]), pack2(S[2 * kp + 1][0], S[2 * kp + 1][1]), pack2(S[2 * kp + 1][2], S[2 * kp + 1][3])});
;                   o0 = __builtin_amdgcn_mfma_f32_16x16x32_bf16(__builtin_bit_cast(bf16x8, (u32x4){qa0.x, qa0.y, qb0.x, qb0.y}), sw, o0, 0, 0, 0);
;                   o1 = __builtin_amdgcn_mfma_f32_16x16x32_bf16(__builtin_bit_cast(bf16x8, (u32x4){qa1.x, qa1.y, qb1.x, qb1.y}), sw, o1, 0, 0, 0); }
; #pragma unroll
;               for (int r = 0; r < 4; ++r) if (g * 4 + r > l15) { sc00[r] = 0.f; sc11[r] = 0.f; }
.LBB0_2441:
	v_pk_mul_f32 v[58:59], v[98:99], v[58:59]
	v_pk_mul_f32 v[56:57], v[96:97], v[56:57]
	ds_read_b128 v[96:99], v160 offset:50176
	v_pk_mul_f32 v[62:63], v[94:95], v[62:63]
	v_pk_mul_f32 v[60:61], v[92:93], v[60:61]
	ds_read_b128 v[68:71], v160 offset:54528
	ds_read_b128 v[92:95], v160 offset:32768
	v_pk_mul_f32 v[46:47], v[110:111], v[46:47]
	v_pk_mul_f32 v[44:45], v[108:109], v[44:45]
	v_pk_mul_f32 v[50:51], v[106:107], v[50:51]
	v_pk_mul_f32 v[48:49], v[104:105], v[48:49]
	v_pk_mul_f32 v[54:55], v[102:103], v[54:55]
	v_pk_mul_f32 v[52:53], v[100:101], v[52:53]
	ds_read_b128 v[100:103], v160 offset:37120
	ds_read_b128 v[104:107], v160 offset:50240
	ds_read_b128 v[108:111], v160 offset:32832
	ds_read_b128 v[162:165], v160 offset:54592
	ds_read_b128 v[166:169], v160 offset:37184
	v_pk_mul_f32 v[66:67], v[90:91], v[66:67]
	s_waitcnt lgkmcnt(5)
	v_mfma_f32_16x16x32_bf16 v[90:93], v[96:99], v[92:95], 0
	v_mul_f32_e64 v64, v88, v64
	v_mul_f32_e64 v65, v89, v65
	v_pk_mul_f32 v[78:79], v[74:75], v[78:79]
	v_pk_mul_f32 v[76:77], v[72:73], v[76:77]
	s_waitcnt lgkmcnt(4)
	v_mfma_f32_16x16x32_bf16 v[170:173], v[68:71], v[100:103], 0
	v_mul_f32_e64 v70, v86, v82
	v_mul_f32_e64 v71, v87, v83
	v_pk_mul_f32 v[68:69], v[84:85], v[80:81]
	ds_read_b128 v[84:87], v160 offset:50304
	s_waitcnt lgkmcnt(3)
	v_mfma_f32_16x16x32_bf16 v[80:83], v[104:107], v[108:111], v[90:93]
	s_nop 2
	ds_read_b128 v[88:91], v160 offset:54656
	ds_read_b128 v[92:95], v160 offset:32896
	v_cvt_pk_bf16_f32 v186, v52, v53
	v_cvt_pk_bf16_f32 v187, v54, v55
	s_waitcnt lgkmcnt(3)
	v_mfma_f32_16x16x32_bf16 v[108:111], v[162:165], v[166:169], v[170:173]
	ds_read_b128 v[162:165], v160 offset:37248
	s_nop 1
	ds_read_b128 v[170:173], v160 offset:50368
	ds_read_b128 v[174:177], v160 offset:32960
	ds_read_b128 v[72:75], v160 offset:54720
	ds_read_b128 v[178:181], v160 offset:37312
	v_cvt_pk_bf16_f32 v188, v56, v57
	s_waitcnt lgkmcnt(4)
	v_mfma_f32_16x16x32_bf16 v[88:91], v[88:91], v[162:165], v[108:111]
	v_cvt_pk_bf16_f32 v189, v58, v59
	s_add_i32 s14, s74, 32
	s_and_b64 s[0:1], s[12:13], exec
	v_mfma_f32_16x16x32_bf16 v[92:95], v[84:87], v[92:95], v[80:83]
	ds_read_b64 v[80:81], v198 offset:31104
	ds_read_b64 v[82:83], v198 offset:31136
	ds_read2_b64 v[108:111], v195 offset1:4
	s_waitcnt lgkmcnt(3)
	v_mfma_f32_16x16x32_bf16 v[72:75], v[72:75], v[178:181], v[88:91]
	v_mov_b32_e32 v0, s39
	ds_read2_b64 v[88:91], v197 offset0:32 offset1:36
	v_mfma_f32_16x16x32_bf16 v[96:99], v[96:99], v[100:103], 0
	s_cselect_b32 s0, s14, s77
	s_add_u32 s0, s50, s0
	v_mfma_f32_16x16x32_bf16 v[92:95], v[170:173], v[174:177], v[92:95]
	v_cvt_pk_bf16_f32 v174, v44, v45
	v_cvt_pk_bf16_f32 v175, v46, v47
	v_cvt_pk_bf16_f32 v176, v48, v49
	v_cvt_pk_bf16_f32 v177, v50, v51
	v_mfma_f32_16x16x32_bf16 v[96:99], v[104:107], v[166:169], v[96:99]
	s_nop 2
	v_cndmask_b32_e64 v0, v92, v0, s[4:5]
	v_cndmask_b32_e64 v0, v0, v92, s[6:7]
	v_cndmask_b32_e64 v3, v94, 0, s[8:9]
	s_waitcnt lgkmcnt(1)
	v_mfma_f32_16x16x32_bf16 v[100:103], v[108:111], v[174:177], 0
	ds_read2_b64 v[108:111], v195 offset0:8 offset1:12
	ds_read2_b64 v[182:185], v197 offset0:40 offset1:44
	ds_read2_b64 v[104:107], v195 offset0:16 offset1:20
	ds_read2_b64 v[166:169], v197 offset0:48 offset1:52
	s_addc_u32 s1, s51, 0
	s_waitcnt lgkmcnt(4)
	v_mfma_f32_16x16x32_bf16 v[88:91], v[88:91], v[174:177], 0
	v_cvt_pk_bf16_f32 v174, v60, v61
	v_cvt_pk_bf16_f32 v175, v62, v63
	v_cvt_pk_bf16_f32 v176, v64, v65
	s_waitcnt lgkmcnt(3)
	v_mfma_f32_16x16x32_bf16 v[100:103], v[108:111], v[186:189], v[100:103]
	v_cvt_pk_bf16_f32 v177, v66, v67
	s_lshl_b64 s[0:1], s[0:1], 11
	v_mfma_f32_16x16x32_bf16 v[84:87], v[84:87], v[162:165], v[96:99]
	s_sub_i32 s38, s38, 64
	s_add_i32 s74, s74, 64
	s_and_b64 vcc, exec, s[54:55]
	s_waitcnt lgkmcnt(2)
	v_mfma_f32_16x16x32_bf16 v[88:91], v[182:185], v[186:189], v[88:91]
	ds_read2_b64 v[108:111], v195 offset0:24 offset1:28
	ds_read2_b64 v[182:185], v197 offset0:56 offset1:60
	v_cvt_pk_bf16_f32 v186, v68, v69
	v_cvt_pk_bf16_f32 v187, v70, v71
	s_waitcnt lgkmcnt(3)
	v_mfma_f32_16x16x32_bf16 v[96:99], v[104:107], v[174:177], v[100:103]
	v_cvt_pk_bf16_f32 v188, v76, v77
	v_cvt_pk_bf16_f32 v189, v78, v79
	s_nop 0
	v_mov_b32_e32 v100, s39
	v_mfma_f32_16x16x32_bf16 v[84:87], v[170:173], v[178:181], v[84:87]
	v_cndmask_b32_e64 v1, v72, v100, s[4:5]
	v_cndmask_b32_e64 v100, v1, v72, s[6:7]
	v_cndmask_b32_e64 v1, 0, v93, s[6:7]
	s_waitcnt lgkmcnt(2)
	v_mfma_f32_16x16x32_bf16 v[88:91], v[166:169], v[174:177], v[88:91]
	v_cndmask_b32_e64 v72, v95, 0, s[10:11]
	v_cvt_pk_bf16_f32 v0, v0, v1
	v_cvt_pk_bf16_f32 v1, v3, v72
	s_waitcnt lgkmcnt(1)
	v_mfma_f32_16x16x32_bf16 v[92:95], v[108:111], v[186:189], v[96:99]
	v_mov_b32_e32 v3, v2
	v_cvt_pk_bf16_f32 v84, v84, v85
	v_cvt_pk_bf16_f32 v85, v86, v87
	v_cndmask_b32_e64 v96, 0, v73, s[6:7]
	v_cndmask_b32_e64 v97, v74, 0, s[8:9]
	v_cndmask_b32_e64 v98, v75, 0, s[10:11]
	v_cvt_pk_bf16_f32 v86, v100, v96
	v_cvt_pk_bf16_f32 v87, v97, v98
	s_waitcnt lgkmcnt(0)
; DI unsigned pack2(float lo, float hi) { const f32x2 v = (f32x2){lo, hi}; return __builtin_bit_cast(unsigned, __builtin_convertvector(v, bf16x2_t)); }
; DI void hgrn_scan_mfma(const Params& p, char* shm) {
;     ...
;               o1 = __builtin_amdgcn_mfma_f32_16x16x32_bf16(__builtin_bit_cast(bf16x8, (u32x4){pack2(sc01[0], sc01[1]), pack2(sc01[2], sc01[3]), pack2(sc11[0], sc11[1]), pack2(sc11[2], sc11[3])}), vf, o1, 0, 0, 0);
; #pragma unroll
;               for (int r = 0; r < 4; ++r) {
;                   const long rb_ = (long)HG_ROW(b, dir, ch * C), st_ = dir ? -(long)D : (long)D; bf16_t* op_ = Oo + rb_ * D + head * 128 + vcol + (long)(g * 4 + r) * st_;
;                   op_[0] = (bf16_t)(pack2(o0[r], 0.f) & 0xffffu); op_[16 * st_] = (bf16_t)(pack2(o1[r], 0.f) & 0xffffu); }
; #pragma unroll
;               for (int kt = 0; kt < 8; ++kt) { const f32x4 dcy = *(const f32x4*)(eBL + kt * 16 + g * 4); const int kcol = kt * 16 + l15;
;                   const bf16x8 kl = __builtin_bit_cast(bf16x8, (u32x4){HG_U2(kt16, g * 4 + 0, g * 4 + 1, kcol), HG_U2(kt16, g * 4 + 2, g * 4 + 3, kcol), HG_U2(kt16, 16 + g * 4 + 0, 16 + g * 4 + 1, kcol), HG_U2(kt16, 16 + g * 4 + 2, 16 + g * 4 + 3, kcol)});
;                   S[kt] = __builtin_amdgcn_mfma_f32_16x16x32_bf16(kl, vf, S[kt], 0, 0, 0) * dcy; }
	v_mfma_f32_16x16x32_bf16 v[88:91], v[182:185], v[186:189], v[88:91]
	v_mfma_f32_16x16x32_bf16 v[72:75], v[0:3], v[80:83], v[92:95]
	v_lshl_add_u64 v[0:1], v[132:133], 0, s[0:1]
	v_mfma_f32_16x16x32_bf16 v[84:87], v[84:87], v[80:83], v[88:91]
	s_nop 4
	v_lshl_add_u64 v[88:89], v[134:135], 1, v[0:1]
	v_cvt_pk_bf16_f32 v3, v72, s0
	global_store_short v[88:89], v3, off
	v_cvt_pk_bf16_f32 v3, v84, s0
	v_lshl_add_u64 v[88:89], v[88:89], 0, s[52:53]
	global_store_short v[88:89], v3, off
	v_lshl_add_u64 v[88:89], v[136:137], 1, v[0:1]
	v_cvt_pk_bf16_f32 v3, v73, s0
	global_store_short v[88:89], v3, off
	v_cvt_pk_bf16_f32 v3, v85, s0
	v_lshl_add_u64 v[72:73], v[88:89], 0, s[52:53]
	global_store_short v[72:73], v3, off
	v_lshl_add_u64 v[72:73], v[138:139], 1, v[0:1]
	v_cvt_pk_bf16_f32 v3, v74, s0
	global_store_short v[72:73], v3, off
	v_cvt_pk_bf16_f32 v3, v86, s0
	v_lshl_add_u64 v[72:73], v[72:73], 0, s[52:53]
	global_store_short v[72:73], v3, off
	v_lshl_add_u64 v[0:1], v[140:141], 1, v[0:1]
	v_cvt_pk_bf16_f32 v3, v75, s0
	global_store_short v[0:1], v3, off
	v_cvt_pk_bf16_f32 v3, v87, s0
	v_lshl_add_u64 v[0:1], v[0:1], 0, s[52:53]
	global_store_short v[0:1], v3, off
	ds_read_b128 v[72:75], v149 offset:58880
	ds_read_b64 v[200:201], v199 offset:20736
	ds_read_b64 v[202:203], v199 offset:20768
	ds_read_b64 v[204:205], v199 offset:22032
	ds_read_b64 v[206:207], v199 offset:22064
	ds_read_b64 v[208:209], v199 offset:23328
	ds_read_b64 v[210:211], v199 offset:23360
	ds_read_b64 v[212:213], v199 offset:24624
	ds_read_b64 v[214:215], v199 offset:24656
	ds_read_b64 v[216:217], v199 offset:25920
	ds_read_b64 v[218:219], v199 offset:25952
	ds_read_b64 v[220:221], v199 offset:27216
	ds_read_b64 v[222:223], v199 offset:27248
	ds_read_b64 v[224:225], v199 offset:28512
	ds_read_b64 v[226:227], v199 offset:28544
	ds_read_b64 v[228:229], v199 offset:29808
	ds_read_b64 v[230:231], v199 offset:29840
	s_waitcnt lgkmcnt(14)
	v_mfma_f32_16x16x32_bf16 v[44:47], v[200:203], v[80:83], v[44:47]
	ds_read_b128 v[84:87], v149 offset:58944
	s_waitcnt lgkmcnt(13)
	v_mfma_f32_16x16x32_bf16 v[48:51], v[204:207], v[80:83], v[48:51]
	s_nop 4
	v_pk_mul_f32 v[46:47], v[74:75], v[46:47]
	v_pk_mul_f32 v[44:45], v[72:73], v[44:45]
	ds_read_b128 v[72:75], v149 offset:59008
	s_waitcnt lgkmcnt(1)
	v_pk_mul_f32 v[50:51], v[86:87], v[50:51]
	v_pk_mul_f32 v[48:49], v[84:85], v[48:49]
	v_mfma_f32_16x16x32_bf16 v[52:55], v[208:211], v[80:83], v[52:55]
	ds_read_b128 v[84:87], v149 offset:59072
	v_mfma_f32_16x16x32_bf16 v[56:59], v[212:215], v[80:83], v[56:59]
	s_nop 4
	s_waitcnt lgkmcnt(1)
	v_pk_mul_f32 v[54:55], v[74:75], v[54:55]
	v_pk_mul_f32 v[52:53], v[72:73], v[52:53]
	ds_read_b128 v[72:75], v149 offset:59136
	s_waitcnt lgkmcnt(1)
	v_pk_mul_f32 v[58:59], v[86:87], v[58:59]
	v_pk_mul_f32 v[56:57], v[84:85], v[56:57]
	v_mfma_f32_16x16x32_bf16 v[60:63], v[216:219], v[80:83], v[60:63]
	ds_read_b128 v[84:87], v149 offset:59200
	v_mfma_f32_16x16x32_bf16 v[64:67], v[220:223], v[80:83], v[64:67]
	s_nop 4
	s_waitcnt lgkmcnt(1)
	v_pk_mul_f32 v[62:63], v[74:75], v[62:63]
	v_pk_mul_f32 v[60:61], v[72:73], v[60:61]
	ds_read_b128 v[72:75], v149 offset:59264
	s_waitcnt lgkmcnt(1)
	v_pk_mul_f32 v[66:67], v[86:87], v[66:67]
	v_pk_mul_f32 v[64:65], v[84:85], v[64:65]
	v_mfma_f32_16x16x32_bf16 v[68:71], v[224:227], v[80:83], v[68:71]
	ds_read_b128 v[84:87], v149 offset:59328
	s_nop 5
	s_waitcnt lgkmcnt(1)
	v_pk_mul_f32 v[74:75], v[74:75], v[70:71]
	v_pk_mul_f32 v[72:73], v[72:73], v[68:69]
	v_mfma_f32_16x16x32_bf16 v[68:71], v[228:231], v[80:83], v[76:79]
	s_nop 6
	s_waitcnt lgkmcnt(0)
	v_pk_mul_f32 v[70:71], v[86:87], v[70:71]
	v_pk_mul_f32 v[68:69], v[84:85], v[68:69]
	s_cbranch_vccnz .LBB0_2411
	s_mov_b32 s76, s75
	s_branch .LBB0_2417
.Lscanh_pro:
	v_cmp_gt_u32_e32 vcc, 0x120, v252
	s_mov_b64 s[2:3], vcc
	s_and_b32 s101, s48, 32
	s_sub_u32 s101, s101, 16
	v_add_u32_e32 v228, 0xffffef00, v158
	v_add_u32_e32 v229, 0xfffff000, v159
	v_and_b32_e32 v230, 15, v252
	v_mul_u32_u24_e32 v230, 0x288, v230
	v_lshl_add_u32 v230, v113, 1, v230
	v_add_u32_e32 v230, 0x10000, v230
	v_add_u32_e32 v231, 0xffffffe0, v230
	v_add_co_u32_e32 v250, vcc, 0xffffc000, v144
	s_nop 1
	v_addc_co_u32_e32 v251, vcc, -1, v145, vcc
	v_cndmask_b32_e64 v0, v150, v113, s[12:13]
	v_add_u32_e32 v0, s101, v0
	v_ashrrev_i32_e32 v1, 31, v0
	v_lshl_add_u64 v[0:1], s[50:51], 0, v[0:1]
	v_lshlrev_b64 v[196:197], 12, v[0:1]
	v_lshlrev_b64 v[0:1], 11, v[0:1]
	v_lshl_add_u64 v[198:199], v[128:129], 0, v[0:1]
	v_lshl_add_u64 v[208:209], v[142:143], 0, v[196:197]
	v_lshl_add_u64 v[0:1], v[130:131], 0, v[0:1]
	global_load_dwordx4 v[196:199], v[198:199], off
	s_nop 0
	global_load_dwordx4 v[200:203], v[208:209], off
	global_load_dwordx4 v[204:207], v[0:1], off
	s_nop 0
	global_load_dwordx4 v[208:211], v[208:209], off offset:2048
	s_and_saveexec_b64 s[14:15], s[2:3]
	s_cbranch_execz .Lscanh_ep0
	global_load_dwordx4 v[4:7], v[250:251], off

.Lscanh_loop:
	s_waitcnt vmcnt(8)
	v_lshlrev_b32_e32 v80, 16, v12
	v_and_b32_e32 v81, 0xffff0000, v12
	v_lshlrev_b32_e32 v82, 16, v16
	v_and_b32_e32 v83, 0xffff0000, v16
	v_lshlrev_b32_e32 v84, 16, v13
	v_and_b32_e32 v85, 0xffff0000, v13
	v_lshlrev_b32_e32 v86, 16, v17
	v_and_b32_e32 v87, 0xffff0000, v17
	v_pk_mul_f32 v[80:81], v[80:81], v[82:83]
	v_pk_mul_f32 v[84:85], v[84:85], v[86:87]
	v_cvt_pk_bf16_f32 v76, v80, v81
	v_cvt_pk_bf16_f32 v77, v84, v85
	v_lshlrev_b32_e32 v80, 16, v14
	v_and_b32_e32 v81, 0xffff0000, v14
	v_lshlrev_b32_e32 v82, 16, v18
	v_and_b32_e32 v83, 0xffff0000, v18
	v_lshlrev_b32_e32 v84, 16, v15
	v_and_b32_e32 v85, 0xffff0000, v15
	v_lshlrev_b32_e32 v86, 16, v19
	v_and_b32_e32 v87, 0xffff0000, v19
	v_pk_mul_f32 v[80:81], v[80:81], v[82:83]
	v_pk_mul_f32 v[84:85], v[84:85], v[86:87]
	v_cvt_pk_bf16_f32 v78, v80, v81
	v_cvt_pk_bf16_f32 v79, v84, v85
	v_lshlrev_b32_e32 v80, 16, v196
	v_and_b32_e32 v81, 0xffff0000, v196
	v_lshlrev_b32_e32 v82, 16, v200
	v_and_b32_e32 v83, 0xffff0000, v200
	v_lshlrev_b32_e32 v84, 16, v197
	v_and_b32_e32 v85, 0xffff0000, v197
	v_lshlrev_b32_e32 v86, 16, v201
	v_and_b32_e32 v87, 0xffff0000, v201
	v_pk_mul_f32 v[80:81], v[80:81], v[82:83]
	v_pk_mul_f32 v[84:85], v[84:85], v[86:87]
	v_cvt_pk_bf16_f32 v246, v80, v81
	v_cvt_pk_bf16_f32 v247, v84, v85
	v_lshlrev_b32_e32 v80, 16, v198
	v_and_b32_e32 v81, 0xffff0000, v198
	v_lshlrev_b32_e32 v82, 16, v202
	v_and_b32_e32 v83, 0xffff0000, v202
	v_lshlrev_b32_e32 v84, 16, v199
	v_and_b32_e32 v85, 0xffff0000, v199
	v_lshlrev_b32_e32 v86, 16, v203
	v_and_b32_e32 v87, 0xffff0000, v203
	v_pk_mul_f32 v[80:81], v[80:81], v[82:83]
	v_pk_mul_f32 v[84:85], v[84:85], v[86:87]
	v_cvt_pk_bf16_f32 v248, v80, v81
	v_cvt_pk_bf16_f32 v249, v84, v85
	ds_write_b128 v158, v[76:79]
	ds_write_b128 v158, v[20:23] offset:8704
	ds_write_b128 v158, v[24:27] offset:17408
	ds_write_b128 v228, v[246:249]
	ds_write_b128 v228, v[204:207] offset:8704
	ds_write_b128 v228, v[208:211] offset:17408
	ds_write_b16 v230, v24 offset:0
	ds_write_b16_d16_hi v230, v24 offset:80
	ds_write_b16 v230, v25 offset:160
	ds_write_b16_d16_hi v230, v25 offset:240
	ds_write_b16 v230, v26 offset:320
	ds_write_b16_d16_hi v230, v26 offset:400
	ds_write_b16 v230, v27 offset:480
	ds_write_b16_d16_hi v230, v27 offset:560
	ds_write_b16 v230, v20 offset:10368
	ds_write_b16_d16_hi v230, v20 offset:10448
	ds_write_b16 v230, v21 offset:10528
	ds_write_b16_d16_hi v230, v21 offset:10608
	ds_write_b16 v230, v22 offset:10688
	ds_write_b16_d16_hi v230, v22 offset:10768
	ds_write_b16 v230, v23 offset:10848
	ds_write_b16_d16_hi v230, v23 offset:10928
	ds_write_b16 v231, v208 offset:0
	ds_write_b16_d16_hi v231, v208 offset:80
	ds_write_b16 v231, v209 offset:160
	ds_write_b16_d16_hi v231, v209 offset:240
	ds_write_b16 v231, v210 offset:320
	ds_write_b16_d16_hi v231, v210 offset:400
	ds_write_b16 v231, v211 offset:480
	ds_write_b16_d16_hi v231, v211 offset:560
	ds_write_b16 v231, v204 offset:10368
	ds_write_b16_d16_hi v231, v204 offset:10448
	ds_write_b16 v231, v205 offset:10528
	ds_write_b16_d16_hi v231, v205 offset:10608
	ds_write_b16 v231, v206 offset:10688
	ds_write_b16_d16_hi v231, v206 offset:10768
	ds_write_b16 v231, v207 offset:10848
	ds_write_b16_d16_hi v231, v207 offset:10928
	s_and_saveexec_b64 s[14:15], s[2:3]
	ds_write_b128 v229, v[4:7] offset:26112
	s_or_b64 exec, exec, s[14:15]
	s_add_i32 s75, s76, 2
	s_cmpk_lt_u32 s76, 0x46
	s_cselect_b64 s[56:57], -1, 0
	s_cmpk_gt_u32 s76, 0x45
	s_cselect_b64 s[54:55], -1, 0
	s_waitcnt lgkmcnt(0)
	s_barrier
	s_and_b64 vcc, exec, s[54:55]
	s_cbranch_vccnz .Lscanh_nopfa
	s_and_b64 vcc, exec, s[12:13]
	v_lshl_add_u32 v0, s75, 5, v113
	s_cbranch_vccnz .Lscanh_ia
	v_add3_u32 v1, v113, s74, 64
	v_cmp_lt_i32_e32 vcc, s47, v1
	s_and_saveexec_b64 s[14:15], vcc
	s_xor_b64 s[14:15], exec, s[14:15]
	v_add_u32_e32 v0, s38, v156
	v_add_u32_e32 v0, 0x9df, v0
	s_andn2_saveexec_b64 s[14:15], s[14:15]
	v_sub_u32_e32 v0, 0xff, v0
	s_or_b64 exec, exec, s[14:15]

.Lscanh_steady:
	s_waitcnt vmcnt(8)
	v_lshlrev_b32_e32 v80, 16, v28
	v_and_b32_e32 v81, 0xffff0000, v28
	v_lshlrev_b32_e32 v82, 16, v32
	v_and_b32_e32 v83, 0xffff0000, v32
	v_lshlrev_b32_e32 v84, 16, v29
	v_and_b32_e32 v85, 0xffff0000, v29
	v_lshlrev_b32_e32 v86, 16, v33
	v_and_b32_e32 v87, 0xffff0000, v33
	v_pk_mul_f32 v[80:81], v[80:81], v[82:83]
	v_pk_mul_f32 v[84:85], v[84:85], v[86:87]
	v_cvt_pk_bf16_f32 v68, v80, v81
	v_cvt_pk_bf16_f32 v69, v84, v85
	v_lshlrev_b32_e32 v80, 16, v30
	v_and_b32_e32 v81, 0xffff0000, v30
	v_lshlrev_b32_e32 v82, 16, v34
	v_and_b32_e32 v83, 0xffff0000, v34
	v_lshlrev_b32_e32 v84, 16, v31
	v_and_b32_e32 v85, 0xffff0000, v31
	v_lshlrev_b32_e32 v86, 16, v35
	v_and_b32_e32 v87, 0xffff0000, v35
	v_pk_mul_f32 v[80:81], v[80:81], v[82:83]
	v_pk_mul_f32 v[84:85], v[84:85], v[86:87]
	v_cvt_pk_bf16_f32 v70, v80, v81
	v_cvt_pk_bf16_f32 v71, v84, v85
	v_lshlrev_b32_e32 v80, 16, v212
	v_and_b32_e32 v81, 0xffff0000, v212
	v_lshlrev_b32_e32 v82, 16, v216
	v_and_b32_e32 v83, 0xffff0000, v216
	v_lshlrev_b32_e32 v84, 16, v213
	v_and_b32_e32 v85, 0xffff0000, v213
	v_lshlrev_b32_e32 v86, 16, v217
	v_and_b32_e32 v87, 0xffff0000, v217
	v_pk_mul_f32 v[80:81], v[80:81], v[82:83]
	v_pk_mul_f32 v[84:85], v[84:85], v[86:87]
	v_cvt_pk_bf16_f32 v246, v80, v81
	v_cvt_pk_bf16_f32 v247, v84, v85
	v_lshlrev_b32_e32 v80, 16, v214
	v_and_b32_e32 v81, 0xffff0000, v214
	v_lshlrev_b32_e32 v82, 16, v218
	v_and_b32_e32 v83, 0xffff0000, v218
	v_lshlrev_b32_e32 v84, 16, v215
	v_and_b32_e32 v85, 0xffff0000, v215
	v_lshlrev_b32_e32 v86, 16, v219
	v_and_b32_e32 v87, 0xffff0000, v219
	v_pk_mul_f32 v[80:81], v[80:81], v[82:83]
	v_pk_mul_f32 v[84:85], v[84:85], v[86:87]
	v_cvt_pk_bf16_f32 v248, v80, v81
	v_cvt_pk_bf16_f32 v249, v84, v85
	ds_write_b128 v158, v[68:71] offset:32768
	ds_write_b128 v158, v[36:39] offset:41472
	ds_write_b128 v158, v[40:43] offset:50176
	ds_write_b128 v228, v[246:249] offset:32768
	ds_write_b128 v228, v[220:223] offset:41472
	ds_write_b128 v228, v[224:227] offset:50176
	ds_write_b16 v230, v40 offset:20736
	ds_write_b16_d16_hi v230, v40 offset:20816
	ds_write_b16 v230, v41 offset:20896
	ds_write_b16_d16_hi v230, v41 offset:20976
	ds_write_b16 v230, v42 offset:21056
	ds_write_b16_d16_hi v230, v42 offset:21136
	ds_write_b16 v230, v43 offset:21216
	ds_write_b16_d16_hi v230, v43 offset:21296
	ds_write_b16 v230, v36 offset:31104
	ds_write_b16_d16_hi v230, v36 offset:31184
	ds_write_b16 v230, v37 offset:31264
	ds_write_b16_d16_hi v230, v37 offset:31344
	ds_write_b16 v230, v38 offset:31424
	ds_write_b16_d16_hi v230, v38 offset:31504
	ds_write_b16 v230, v39 offset:31584
	ds_write_b16_d16_hi v230, v39 offset:31664
	ds_write_b16 v231, v224 offset:20736
	ds_write_b16_d16_hi v231, v224 offset:20816
	ds_write_b16 v231, v225 offset:20896
	ds_write_b16_d16_hi v231, v225 offset:20976
	ds_write_b16 v231, v226 offset:21056
	ds_write_b16_d16_hi v231, v226 offset:21136
	ds_write_b16 v231, v227 offset:21216
	ds_write_b16_d16_hi v231, v227 offset:21296
	ds_write_b16 v231, v220 offset:31104
	ds_write_b16_d16_hi v231, v220 offset:31184
	ds_write_b16 v231, v221 offset:31264
	ds_write_b16_d16_hi v231, v221 offset:31344
	ds_write_b16 v231, v222 offset:31424
	ds_write_b16_d16_hi v231, v222 offset:31504
	ds_write_b16 v231, v223 offset:31584
	ds_write_b16_d16_hi v231, v223 offset:31664
	s_and_saveexec_b64 s[14:15], s[2:3]
	ds_write_b128 v229, v[8:11] offset:58880
	s_or_b64 exec, exec, s[14:15]
	s_waitcnt lgkmcnt(0)
	s_barrier
	s_andn2_b64 vcc, exec, s[56:57]
	s_cbranch_vccnz .Lscanh_nopfb
	s_lshl_b32 s14, s76, 5
	s_addk_i32 s14, 0x60
	s_and_b64 vcc, exec, s[12:13]
	v_add_u32_e32 v0, s14, v113
	s_cbranch_vccnz .Lscanh_ib
	v_add_u32_e32 v1, s74, v113
	v_add_u32_e32 v1, 0x60, v1
	v_cmp_lt_i32_e32 vcc, s47, v1
	s_and_saveexec_b64 s[14:15], vcc
	s_xor_b64 s[14:15], exec, s[14:15]
	v_add_u32_e32 v0, s38, v156
	v_add_u32_e32 v0, 0x9bf, v0
	s_andn2_saveexec_b64 s[14:15], s[14:15]
	v_sub_u32_e32 v0, 0xff, v0
	s_or_b64 exec, exec, s[14:15]
